# p3a S1: dead address arithmetic of the removed ds_bpermute reductions deleted (17 VALU per k-head iteration); hazard-clean
# speedup vs baseline: 1.0068x; 1.0068x over previous
.Lp3a_s2h_skip:
	v_pk_fma_f32 v[52:53], v[110:111], v[48:49], v[52:53]
	v_pk_add_f32 v[226:227], v[226:227], 1.0 op_sel_hi:[1,0]
	v_pk_mul_f32 v[228:229], v[52:53], v[246:247] op_sel_hi:[1,0]
	v_rcp_f32_e32 v226, v226
	v_rcp_f32_e32 v227, v227
	v_exp_f32_e32 v228, v228
	v_exp_f32_e32 v229, v229
	v_lshlrev_b32_e32 v28, 16, v121
	v_pk_mul_f32 v[22:23], v[22:23], v[226:227]
	v_pk_add_f32 v[228:229], v[228:229], 1.0 op_sel_hi:[1,0]
	v_lshlrev_b32_e32 v54, 16, v117
	v_and_b32_e32 v55, 0xffff0000, v117
	v_and_b32_e32 v29, 0xffff0000, v121
	v_pk_fma_f32 v[54:55], v[4:5], v[54:55], 0 op_sel_hi:[1,1,0]
	v_lshlrev_b32_e32 v36, 16, v125
	v_and_b32_e32 v37, 0xffff0000, v125
	v_pk_fma_f32 v[54:55], v[16:17], v[28:29], v[54:55]
	v_lshlrev_b32_e32 v44, 16, v129
	v_and_b32_e32 v45, 0xffff0000, v129
	v_pk_fma_f32 v[54:55], v[104:105], v[36:37], v[54:55]
	v_rcp_f32_e32 v228, v228
	v_pk_fma_f32 v[54:55], v[112:113], v[44:45], v[54:55]
	v_rcp_f32_e32 v229, v229
	v_pk_mul_f32 v[226:227], v[54:55], v[246:247] op_sel_hi:[1,0]
	v_exp_f32_e32 v226, v226
	v_exp_f32_e32 v227, v227
	v_pk_mul_f32 v[232:233], v[20:21], v[20:21]
	v_pk_fma_f32 v[232:233], v[22:23], v[22:23], v[232:233]
	v_pk_add_f32 v[226:227], v[226:227], 1.0 op_sel_hi:[1,0]
	v_rcp_f32_e32 v226, v226
	v_rcp_f32_e32 v227, v227
	v_pk_mul_f32 v[52:53], v[52:53], v[228:229]
	v_and_b32_e32 v167, 64, v184
	v_pk_fma_f32 v[232:233], v[52:53], v[52:53], v[232:233]
	v_pk_mul_f32 v[54:55], v[54:55], v[226:227]
	v_pk_fma_f32 v[232:233], v[54:55], v[54:55], v[232:233]
	v_add_f32_e32 v24, v232, v233
	v_mov_b32_e32 v160, v1
	s_nop 1
	v_add_f32_dpp v24, v24, v24 quad_perm:[1,0,3,2] row_mask:0xf bank_mask:0xf
	v_cmp_gt_i32_e64 s[6:7], 16, v160
	v_mov_b32_e32 v56, 1.0
	s_nop 1
	v_add_f32_dpp v24, v24, v24 quad_perm:[2,3,0,1] row_mask:0xf bank_mask:0xf
	v_cndmask_b32_e64 v161, 1.0, v187, s[6:7]
	v_cmp_gt_i32_e64 s[4:5], 32, v160
	s_nop 1
	v_add_f32_dpp v24, v24, v24 row_half_mirror row_mask:0xf bank_mask:0xf
	s_nop 1
	v_add_f32_dpp v24, v24, v24 row_mirror row_mask:0xf bank_mask:0xf
	s_and_saveexec_b64 s[8:9], s[4:5]
	s_cbranch_execz .LBB0_502
	v_add_f32_e32 v24, 0x358637bd, v24
	v_mul_f32_e32 v25, 0x4b800000, v24
	v_cmp_gt_f32_e32 vcc, s48, v24
	s_nop 1
	v_cndmask_b32_e32 v24, v24, v25, vcc
	v_rsq_f32_e32 v24, v24
	s_nop 0
	v_mul_f32_e32 v25, 0x45800000, v24
	v_cndmask_b32_e32 v24, v24, v25, vcc
	v_mul_f32_e32 v56, v161, v24
